# DF epilogue: packed f32 ops split into scalar ops as in the loops
# baseline (speedup 1.0000x reference)
.LBB0_460:
	s_waitcnt lgkmcnt(0)
	s_barrier
	s_and_b64 vcc, exec, s[4:5]
	s_cbranch_vccnz .LBB0_299
	v_mov_b32_e32 v2, v217
	s_nop 1
	v_permlane32_swap_b32_e32 v217, v2
	v_add_f32_e32 v2, v217, v2
	v_div_scale_f32 v3, s[2:3], v2, v2, 1.0
	v_rcp_f32_e32 v4, v3
	s_waitcnt vmcnt(3)
	v_min_u32_e32 v253, 0xffff, v253
	v_or_b32_e32 v95, v95, v253
	v_lshlrev_b32_e32 v110, 16, v107
	v_and_b32_e32 v111, 0xffff0000, v107
	s_lshl_b64 s[2:3], s[6:7], 22
	v_fma_f32 v5, -v3, v4, 1.0
	v_fmac_f32_e32 v4, v5, v4
	v_div_scale_f32 v5, vcc, 1.0, v2, 1.0
	v_mul_f32_e32 v6, v5, v4
	v_fma_f32 v7, -v3, v6, v5
	v_fmac_f32_e32 v6, v7, v4
	v_fma_f32 v3, -v3, v6, v5
	v_div_fmas_f32 v3, v3, v4, v6
	v_div_fixup_f32 v94, v3, v2, 1.0
	ds_read2st64_b32 v[100:101], v0 offset1:1
	ds_read2st64_b32 v[98:99], v0 offset0:2 offset1:3
	ds_read2st64_b32 v[112:113], v0 offset0:4 offset1:5
	ds_read2st64_b32 v[108:109], v0 offset0:6 offset1:7
	ds_read2st64_b32 v[124:125], v0 offset0:8 offset1:9
	ds_read2st64_b32 v[128:129], v0 offset0:10 offset1:11
	ds_read2st64_b32 v[138:139], v0 offset0:12 offset1:13
	ds_read2st64_b32 v[186:187], v0 offset0:14 offset1:15
	ds_read2st64_b32 v[140:141], v0 offset0:16 offset1:17
	ds_read2st64_b32 v[136:137], v0 offset0:18 offset1:19
	ds_read2st64_b32 v[188:189], v0 offset0:20 offset1:21
	ds_read2st64_b32 v[194:195], v0 offset0:22 offset1:23
	ds_read2st64_b32 v[200:201], v0 offset0:24 offset1:25
	ds_read2st64_b32 v[192:193], v0 offset0:26 offset1:27
	ds_read2st64_b32 v[210:211], v0 offset0:28 offset1:29
	ds_read2st64_b32 v[202:203], v0 offset0:30 offset1:31
	ds_read2st64_b32 v[216:217], v0 offset0:32 offset1:33
	ds_read2st64_b32 v[212:213], v0 offset0:34 offset1:35
	ds_read2st64_b32 v[204:205], v0 offset0:36 offset1:37
	ds_read2st64_b32 v[208:209], v0 offset0:38 offset1:39
	ds_read2st64_b32 v[190:191], v0 offset0:40 offset1:41
	ds_read2st64_b32 v[198:199], v0 offset0:42 offset1:43
	ds_read2st64_b32 v[180:181], v0 offset0:44 offset1:45
	ds_read2st64_b32 v[182:183], v0 offset0:46 offset1:47
	ds_read2st64_b32 v[114:115], v0 offset0:56 offset1:57
	ds_read2st64_b32 v[116:117], v0 offset0:58 offset1:59
	ds_read2st64_b32 v[102:103], v0 offset0:60 offset1:61
	ds_read2st64_b32 v[2:3], v0 offset0:62 offset1:63
	ds_read2st64_b32 v[142:143], v0 offset0:48 offset1:49
	ds_read2st64_b32 v[144:145], v0 offset0:50 offset1:51
	ds_read2st64_b32 v[126:127], v0 offset0:52 offset1:53
	ds_read2st64_b32 v[130:131], v0 offset0:54 offset1:55
	s_waitcnt lgkmcnt(14)
	v_fma_f32 v100, v64, v94, -v100
	v_fma_f32 v101, v65, v94, -v101
	v_lshlrev_b32_e32 v64, 16, v106
	s_waitcnt lgkmcnt(4)
	v_fma_f32 v86, v30, v94, -v2
	v_fma_f32 v87, v31, v94, -v3
	v_and_b32_e32 v65, 0xffff0000, v106
	v_mul_f32_e32 v31, 0xbfb8aa3b, v64
	v_fma_f32 v98, v66, v94, -v98
	v_fma_f32 v99, v67, v94, -v99
	v_exp_f32_e32 v66, v31
	v_mul_f32_e32 v31, 0xbfb8aa3b, v65
	v_exp_f32_e32 v67, v31
	v_mul_f32_e32 v106, 0xbfb8aa3b, v110
	v_add_f32_e32 v66, 1.0, v66
	v_exp_f32_e32 v118, v106
	v_add_f32_e32 v67, 1.0, v67
	v_mul_f32_e32 v106, 0xbfb8aa3b, v111
	v_rcp_f32_e32 v66, v66
	v_rcp_f32_e32 v67, v67
	v_exp_f32_e32 v119, v106
	v_mul_f32_e32 v30, v101, v101
	v_fma_f32 v31, v101, v101, v30
	v_fma_f32 v30, v100, v100, v30
	v_mul_f32 v106, v66, v64
	v_mul_f32 v107, v67, v65
	v_add_f32_e32 v64, 1.0, v118
	v_add_f32_e32 v65, 1.0, v119
	v_rcp_f32_e32 v64, v64
	v_rcp_f32_e32 v65, v65
	v_fma_f32 v30, v98, v98, v30
	v_fma_f32 v31, v99, v99, v31
	v_mul_f32_e32 v66, v99, v99
	v_add_f32 v30, v66, v30
	v_add_f32 v31, v66, v31
	v_lshlrev_b32_e32 v66, 16, v12
	v_and_b32_e32 v67, 0xffff0000, v12
	v_mul_f32_e32 v12, 0xbfb8aa3b, v66
	v_mul_f32 v110, v64, v110
	v_mul_f32 v111, v65, v111
	v_exp_f32_e32 v12, v12
	v_mul_f32_e32 v65, 0xbfb8aa3b, v67
	v_exp_f32_e32 v65, v65
	v_fma_f32 v112, v68, v94, -v112
	v_fma_f32 v113, v69, v94, -v113
	v_add_f32_e32 v12, 1.0, v12
	v_fma_f32 v30, v112, v112, v30
	v_fma_f32 v31, v113, v113, v31
	v_mul_f32_e32 v64, v113, v113
	v_add_f32 v30, v64, v30
	v_add_f32 v31, v64, v31
	v_rcp_f32_e32 v64, v12
	v_add_f32_e32 v12, 1.0, v65
	v_rcp_f32_e32 v65, v12
	v_lshlrev_b32_e32 v12, 16, v13
	v_and_b32_e32 v13, 0xffff0000, v13
	v_mul_f32_e32 v68, 0xbfb8aa3b, v12
	v_mul_f32_e32 v69, 0xbfb8aa3b, v13
	v_exp_f32_e32 v68, v68
	v_exp_f32_e32 v69, v69
	v_mul_f32 v118, v64, v66
	v_mul_f32 v119, v65, v67
	v_fma_f32 v108, v70, v94, -v108
	v_fma_f32 v109, v71, v94, -v109
	v_add_f32_e32 v64, 1.0, v68
	v_add_f32_e32 v65, 1.0, v69
	v_rcp_f32_e32 v64, v64
	v_rcp_f32_e32 v65, v65
	v_fma_f32 v30, v108, v108, v30
	v_fma_f32 v31, v109, v109, v31
	v_mul_f32_e32 v66, v109, v109
	v_add_f32 v30, v66, v30
	v_add_f32 v31, v66, v31
	v_mul_f32 v122, v64, v12
	v_mul_f32 v123, v65, v13
	v_lshlrev_b32_e32 v64, 16, v10
	v_fma_f32 v72, v72, v94, -v124
	v_fma_f32 v73, v73, v94, -v125
	v_and_b32_e32 v65, 0xffff0000, v10
	v_mul_f32_e32 v10, 0xbfb8aa3b, v64
	v_fma_f32 v12, v72, v72, v30
	v_fma_f32 v13, v73, v73, v31
	v_exp_f32_e32 v10, v10
	v_mul_f32_e32 v31, 0xbfb8aa3b, v65
	v_exp_f32_e32 v31, v31
	v_mul_f32_e32 v30, v73, v73
	v_add_f32_e32 v10, 1.0, v10
	v_fma_f32 v74, v74, v94, -v128
	v_fma_f32 v75, v75, v94, -v129
	v_add_f32 v12, v30, v12
	v_add_f32 v13, v30, v13
	v_rcp_f32_e32 v30, v10
	v_add_f32_e32 v10, 1.0, v31
	v_rcp_f32_e32 v31, v10
	v_lshlrev_b32_e32 v10, 16, v11
	v_and_b32_e32 v11, 0xffff0000, v11
	v_mul_f32_e32 v66, 0xbfb8aa3b, v10
	v_mul_f32_e32 v67, 0xbfb8aa3b, v11
	v_exp_f32_e32 v66, v66
	v_exp_f32_e32 v67, v67
	v_mul_f32 v124, v30, v64
	v_mul_f32 v125, v31, v65
	v_fma_f32 v12, v74, v74, v12
	v_fma_f32 v13, v75, v75, v13
	v_add_f32_e32 v30, 1.0, v66
	v_add_f32_e32 v31, 1.0, v67
	v_rcp_f32_e32 v30, v30
	v_rcp_f32_e32 v31, v31
	v_mul_f32_e32 v64, v75, v75
	v_add_f32 v68, v64, v12
	v_add_f32 v69, v64, v13
	v_fma_f32 v76, v76, v94, -v138
	v_fma_f32 v77, v77, v94, -v139
	v_lshlrev_b32_e32 v70, 16, v134
	v_and_b32_e32 v71, 0xffff0000, v134
	v_mul_f32 v128, v30, v10
	v_mul_f32 v129, v31, v11
	v_fma_f32 v30, v76, v76, v68
	v_fma_f32 v31, v77, v77, v69
	v_mul_f32_e32 v69, 0xbfb8aa3b, v70
	v_mul_f32_e32 v134, 0xbfb8aa3b, v71
	v_exp_f32_e32 v69, v69
	v_exp_f32_e32 v134, v134
	v_mul_f32_e32 v68, v77, v77
	v_lshlrev_b32_e32 v138, 16, v135
	v_add_f32 v30, v68, v30
	v_add_f32 v31, v68, v31
	v_add_f32_e32 v68, 1.0, v69
	v_add_f32_e32 v69, 1.0, v134
	v_and_b32_e32 v139, 0xffff0000, v135
	v_mul_f32_e32 v134, 0xbfb8aa3b, v138
	v_exp_f32_e32 v148, v134
	v_mul_f32_e32 v134, 0xbfb8aa3b, v139
	v_rcp_f32_e32 v68, v68
	v_rcp_f32_e32 v69, v69
	v_exp_f32_e32 v149, v134
	v_fma_f32 v136, v50, v94, -v136
	v_fma_f32 v137, v51, v94, -v137
	v_lshlrev_b32_e32 v50, 16, v184
	v_mul_f32 v134, v68, v70
	v_mul_f32 v135, v69, v71
	v_add_f32_e32 v68, 1.0, v148
	v_add_f32_e32 v69, 1.0, v149
	v_rcp_f32_e32 v68, v68
	v_rcp_f32_e32 v69, v69
	v_and_b32_e32 v51, 0xffff0000, v184
	v_fma_f32 v140, v48, v94, -v140
	v_fma_f32 v141, v49, v94, -v141
	v_mul_f32_e32 v49, 0xbfb8aa3b, v50
	v_mul_f32 v138, v68, v138
	v_mul_f32 v139, v69, v139
	v_mul_f32_e32 v68, 0xbfb8aa3b, v51
	v_fma_f32 v78, v78, v94, -v186
	v_fma_f32 v79, v79, v94, -v187
	v_exp_f32_e32 v49, v49
	v_exp_f32_e32 v68, v68
	v_fma_f32 v30, v78, v78, v30
	v_fma_f32 v31, v79, v79, v31
	v_mul_f32_e32 v70, v79, v79
	v_add_f32 v30, v70, v30
	v_add_f32 v31, v70, v31
	v_fma_f32 v30, v140, v140, v30
	v_fma_f32 v31, v141, v141, v31
	v_mul_f32_e32 v48, v141, v141
	v_add_f32 v30, v48, v30
	v_add_f32 v31, v48, v31
	v_add_f32_e32 v48, 1.0, v49
	v_add_f32_e32 v49, 1.0, v68
	v_lshlrev_b32_e32 v0, 11, v179
	v_rcp_f32_e32 v48, v48
	v_rcp_f32_e32 v49, v49
	v_lshl_add_u64 v[2:3], s[56:57], 0, v[0:1]
	v_lshlrev_b32_e32 v68, 16, v185
	v_and_b32_e32 v69, 0xffff0000, v185
	v_fma_f32 v184, v54, v94, -v194
	v_fma_f32 v185, v55, v94, -v195
	v_lshlrev_b32_e32 v54, 16, v146
	v_and_b32_e32 v55, 0xffff0000, v146
	v_lshl_add_u64 v[2:3], v[2:3], 0, s[2:3]
	s_lshl_b32 s80, s16, 8
	v_fma_f32 v188, v52, v94, -v188
	v_fma_f32 v189, v53, v94, -v189
	v_mul_f32_e32 v53, 0xbfb8aa3b, v54
	v_mul_f32_e32 v146, 0xbfb8aa3b, v55
	v_lshl_add_u64 v[2:3], v[2:3], 0, s[80:81]
	v_ashrrev_i32_e32 v179, 31, v178
	v_exp_f32_e32 v53, v53
	v_exp_f32_e32 v146, v146
	v_lshl_add_u64 v[88:89], v[178:179], 1, v[2:3]
	v_lshl_add_u32 v0, v178, 2, 0
	v_mul_f32 v178, v48, v50
	v_mul_f32 v179, v49, v51
	v_fma_f32 v30, v136, v136, v30
	v_fma_f32 v31, v137, v137, v31
	v_mul_f32_e32 v50, v137, v137
	v_add_f32 v30, v50, v30
	v_add_f32 v31, v50, v31
	v_fma_f32 v30, v188, v188, v30
	v_fma_f32 v31, v189, v189, v31
	v_mul_f32_e32 v52, v189, v189
	v_lshlrev_b32_e32 v148, 16, v147
	v_add_f32 v30, v52, v30
	v_add_f32 v31, v52, v31
	v_add_f32_e32 v52, 1.0, v53
	v_add_f32_e32 v53, 1.0, v146
	v_and_b32_e32 v149, 0xffff0000, v147
	v_mul_f32_e32 v146, 0xbfb8aa3b, v148
	v_exp_f32_e32 v150, v146
	v_mul_f32_e32 v146, 0xbfb8aa3b, v149
	v_rcp_f32_e32 v52, v52
	v_rcp_f32_e32 v53, v53
	v_exp_f32_e32 v151, v146
	v_fma_f32 v30, v184, v184, v30
	v_fma_f32 v31, v185, v185, v31
	v_fma_f32 v200, v56, v94, -v200
	v_fma_f32 v201, v57, v94, -v201
	v_mul_f32 v146, v52, v54
	v_mul_f32 v147, v53, v55
	v_add_f32_e32 v52, 1.0, v150
	v_add_f32_e32 v53, 1.0, v151
	v_rcp_f32_e32 v52, v52
	v_rcp_f32_e32 v53, v53
	v_mul_f32_e32 v54, v185, v185
	v_add_f32 v30, v54, v30
	v_add_f32 v31, v54, v31
	v_lshlrev_b32_e32 v54, 16, v132
	v_and_b32_e32 v55, 0xffff0000, v132
	v_mul_f32 v194, v52, v148
	v_mul_f32 v195, v53, v149
	v_mul_f32_e32 v53, 0xbfb8aa3b, v54
	v_mul_f32_e32 v56, 0xbfb8aa3b, v55
	v_exp_f32_e32 v53, v53
	v_exp_f32_e32 v56, v56
	v_fma_f32 v30, v200, v200, v30
	v_fma_f32 v31, v201, v201, v31
	v_mul_f32_e32 v52, v201, v201
	v_add_f32 v30, v52, v30
	v_add_f32 v31, v52, v31
	v_add_f32_e32 v52, 1.0, v53
	v_add_f32_e32 v53, 1.0, v56
	v_rcp_f32_e32 v52, v52
	v_rcp_f32_e32 v53, v53
	v_fma_f32 v202, v62, v94, -v202
	v_fma_f32 v203, v63, v94, -v203
	v_lshlrev_b32_e32 v62, 16, v120
	v_and_b32_e32 v63, 0xffff0000, v120
	v_fma_f32 v210, v60, v94, -v210
	v_fma_f32 v211, v61, v94, -v211
	v_mul_f32_e32 v61, 0xbfb8aa3b, v62
	v_mul_f32_e32 v120, 0xbfb8aa3b, v63
	v_fma_f32 v192, v58, v94, -v192
	v_fma_f32 v193, v59, v94, -v193
	v_exp_f32_e32 v61, v61
	v_exp_f32_e32 v120, v120
	v_lshlrev_b32_e32 v56, 16, v133
	v_and_b32_e32 v57, 0xffff0000, v133
	v_mul_f32 v132, v52, v54
	v_mul_f32 v133, v53, v55
	v_fma_f32 v30, v192, v192, v30
	v_fma_f32 v31, v193, v193, v31
	v_mul_f32_e32 v54, v193, v193
	v_add_f32 v30, v54, v30
	v_add_f32 v31, v54, v31
	v_fma_f32 v30, v210, v210, v30
	v_fma_f32 v31, v211, v211, v31
	v_mul_f32_e32 v60, v211, v211
	v_lshlrev_b32_e32 v148, 16, v121
	v_add_f32 v30, v60, v30
	v_add_f32 v31, v60, v31
	v_add_f32_e32 v60, 1.0, v61
	v_add_f32_e32 v61, 1.0, v120
	v_and_b32_e32 v149, 0xffff0000, v121
	v_mul_f32_e32 v120, 0xbfb8aa3b, v148
	v_exp_f32_e32 v150, v120
	v_mul_f32_e32 v120, 0xbfb8aa3b, v149
	v_rcp_f32_e32 v60, v60
	v_rcp_f32_e32 v61, v61
	v_exp_f32_e32 v151, v120
	v_fma_f32 v212, v34, v94, -v212
	v_fma_f32 v213, v35, v94, -v213
	v_lshlrev_b32_e32 v34, 16, v104
	v_mul_f32 v120, v60, v62
	v_mul_f32 v121, v61, v63
	v_add_f32_e32 v60, 1.0, v150
	v_add_f32_e32 v61, 1.0, v151
	v_rcp_f32_e32 v60, v60
	v_rcp_f32_e32 v61, v61
	v_and_b32_e32 v35, 0xffff0000, v104
	v_fma_f32 v216, v32, v94, -v216
	v_fma_f32 v217, v33, v94, -v217
	v_mul_f32_e32 v33, 0xbfb8aa3b, v34
	v_mul_f32 v214, v60, v148
	v_mul_f32 v215, v61, v149
	v_mul_f32_e32 v60, 0xbfb8aa3b, v35
	v_exp_f32_e32 v33, v33
	v_exp_f32_e32 v60, v60
	v_fma_f32 v30, v202, v202, v30
	v_fma_f32 v31, v203, v203, v31
	v_mul_f32_e32 v62, v203, v203
	v_add_f32 v30, v62, v30
	v_add_f32 v31, v62, v31
	v_fma_f32 v30, v216, v216, v30
	v_fma_f32 v31, v217, v217, v31
	v_mul_f32_e32 v32, v217, v217
	v_add_f32 v30, v32, v30
	v_add_f32 v31, v32, v31
	v_add_f32_e32 v32, 1.0, v33
	v_add_f32_e32 v33, 1.0, v60
	v_rcp_f32_e32 v32, v32
	v_rcp_f32_e32 v33, v33
	v_fma_f32 v208, v38, v94, -v208
	v_fma_f32 v209, v39, v94, -v209
	v_lshlrev_b32_e32 v38, 16, v96
	v_and_b32_e32 v39, 0xffff0000, v96
	v_fma_f32 v204, v36, v94, -v204
	v_fma_f32 v205, v37, v94, -v205
	v_mul_f32_e32 v37, 0xbfb8aa3b, v38
	v_mul_f32_e32 v96, 0xbfb8aa3b, v39
	v_exp_f32_e32 v37, v37
	v_exp_f32_e32 v96, v96
	v_lshlrev_b32_e32 v60, 16, v105
	v_and_b32_e32 v61, 0xffff0000, v105
	v_mul_f32 v104, v32, v34
	v_mul_f32 v105, v33, v35
	v_fma_f32 v30, v212, v212, v30
	v_fma_f32 v31, v213, v213, v31
	v_mul_f32_e32 v34, v213, v213
	v_add_f32 v35, v34, v31
	v_add_f32 v34, v34, v30
	v_fma_f32 v34, v204, v204, v34
	v_fma_f32 v35, v205, v205, v35
	v_mul_f32_e32 v36, v205, v205
	v_lshlrev_b32_e32 v148, 16, v97
	v_add_f32 v34, v36, v34
	v_add_f32 v35, v36, v35
	v_add_f32_e32 v36, 1.0, v37
	v_add_f32_e32 v37, 1.0, v96
	v_and_b32_e32 v149, 0xffff0000, v97
	v_mul_f32_e32 v96, 0xbfb8aa3b, v148
	v_exp_f32_e32 v150, v96
	v_mul_f32_e32 v96, 0xbfb8aa3b, v149
	v_rcp_f32_e32 v36, v36
	v_rcp_f32_e32 v37, v37
	v_exp_f32_e32 v151, v96
	v_fma_f32 v34, v208, v208, v34
	v_fma_f32 v35, v209, v209, v35
	v_fma_f32 v190, v40, v94, -v190
	v_fma_f32 v191, v41, v94, -v191
	v_mul_f32 v96, v36, v38
	v_mul_f32 v97, v37, v39
	v_add_f32_e32 v36, 1.0, v150
	v_add_f32_e32 v37, 1.0, v151
	v_rcp_f32_e32 v36, v36
	v_rcp_f32_e32 v37, v37
	v_mul_f32_e32 v38, v209, v209
	v_add_f32 v34, v38, v34
	v_add_f32 v35, v38, v35
	v_lshlrev_b32_e32 v38, 16, v92
	v_and_b32_e32 v39, 0xffff0000, v92
	v_mul_f32 v220, v36, v148
	v_mul_f32 v221, v37, v149
	v_mul_f32_e32 v37, 0xbfb8aa3b, v38
	v_mul_f32_e32 v40, 0xbfb8aa3b, v39
	v_exp_f32_e32 v37, v37
	v_exp_f32_e32 v40, v40
	v_fma_f32 v34, v190, v190, v34
	v_fma_f32 v35, v191, v191, v35
	v_mul_f32_e32 v36, v191, v191
	v_add_f32 v34, v36, v34
	v_add_f32 v35, v36, v35
	v_add_f32_e32 v36, 1.0, v37
	v_add_f32_e32 v37, 1.0, v40
	v_lshlrev_b32_e32 v40, 16, v93
	v_and_b32_e32 v41, 0xffff0000, v93
	v_fma_f32 v198, v42, v94, -v198
	v_fma_f32 v199, v43, v94, -v199
	v_rcp_f32_e32 v36, v36
	v_rcp_f32_e32 v37, v37
	v_mul_f32_e32 v42, 0xbfb8aa3b, v40
	v_mul_f32_e32 v43, 0xbfb8aa3b, v41
	v_exp_f32_e32 v42, v42
	v_exp_f32_e32 v43, v43
	v_lshlrev_b32_e32 v148, 16, v90
	v_and_b32_e32 v149, 0xffff0000, v90
	v_fma_f32 v180, v44, v94, -v180
	v_fma_f32 v181, v45, v94, -v181
	v_mul_f32_e32 v45, 0xbfb8aa3b, v148
	v_mul_f32_e32 v90, 0xbfb8aa3b, v149
	v_exp_f32_e32 v45, v45
	v_exp_f32_e32 v90, v90
	v_mul_f32 v92, v36, v38
	v_mul_f32 v93, v37, v39
	v_fma_f32 v34, v198, v198, v34
	v_fma_f32 v35, v199, v199, v35
	v_mul_f32_e32 v38, v199, v199
	v_add_f32_e32 v36, 1.0, v42
	v_add_f32_e32 v37, 1.0, v43
	v_add_f32 v42, v38, v34
	v_add_f32 v43, v38, v35
	v_fma_f32 v42, v180, v180, v42
	v_fma_f32 v43, v181, v181, v43
	v_mul_f32_e32 v44, v181, v181
	v_lshlrev_b32_e32 v150, 16, v91
	v_add_f32 v42, v44, v42
	v_add_f32 v43, v44, v43
	v_add_f32_e32 v44, 1.0, v45
	v_add_f32_e32 v45, 1.0, v90
	v_and_b32_e32 v151, 0xffff0000, v91
	v_mul_f32_e32 v90, 0xbfb8aa3b, v150
	v_fma_f32 v46, v46, v94, -v182
	v_fma_f32 v47, v47, v94, -v183
	v_exp_f32_e32 v182, v90
	v_mul_f32_e32 v90, 0xbfb8aa3b, v151
	v_rcp_f32_e32 v44, v44
	v_rcp_f32_e32 v45, v45
	v_exp_f32_e32 v183, v90
	v_fma_f32 v42, v46, v46, v42
	v_fma_f32 v43, v47, v47, v43
	s_waitcnt lgkmcnt(3)
	v_fma_f32 v142, v16, v94, -v142
	v_fma_f32 v143, v17, v94, -v143
	v_mul_f32 v90, v44, v148
	v_mul_f32 v91, v45, v149
	v_add_f32_e32 v44, 1.0, v182
	v_add_f32_e32 v45, 1.0, v183
	v_rcp_f32_e32 v44, v44
	v_rcp_f32_e32 v45, v45
	v_mul_f32_e32 v148, v47, v47
	v_add_f32 v42, v148, v42
	v_add_f32 v43, v148, v43
	v_fma_f32 v16, v142, v142, v42
	v_fma_f32 v17, v143, v143, v43
	v_mul_f32 v182, v44, v150
	v_mul_f32 v183, v45, v151
	v_lshlrev_b32_e32 v44, 16, v14
	v_and_b32_e32 v45, 0xffff0000, v14
	v_mul_f32_e32 v14, 0xbfb8aa3b, v44
	v_exp_f32_e32 v14, v14
	v_mul_f32_e32 v43, 0xbfb8aa3b, v45
	v_exp_f32_e32 v43, v43
	v_mul_f32_e32 v42, v143, v143
	v_add_f32_e32 v14, 1.0, v14
	s_waitcnt lgkmcnt(2)
	v_fma_f32 v18, v18, v94, -v144
	v_fma_f32 v19, v19, v94, -v145
	v_add_f32 v16, v42, v16
	v_add_f32 v17, v42, v17
	v_rcp_f32_e32 v42, v14
	v_add_f32_e32 v14, 1.0, v43
	v_rcp_f32_e32 v43, v14
	v_lshlrev_b32_e32 v14, 16, v15
	v_and_b32_e32 v15, 0xffff0000, v15
	v_mul_f32_e32 v144, 0xbfb8aa3b, v14
	v_exp_f32_e32 v148, v144
	v_mul_f32_e32 v144, 0xbfb8aa3b, v15
	v_exp_f32_e32 v149, v144
	v_mul_f32 v144, v42, v44
	v_mul_f32 v145, v43, v45
	v_fma_f32 v16, v18, v18, v16
	v_fma_f32 v17, v19, v19, v17
	v_mul_f32_e32 v44, v19, v19
	v_add_f32_e32 v42, 1.0, v148
	v_add_f32_e32 v43, 1.0, v149
	v_add_f32 v148, v44, v16
	v_add_f32 v149, v44, v17
	s_waitcnt lgkmcnt(1)
	v_fma_f32 v20, v20, v94, -v126
	v_fma_f32 v21, v21, v94, -v127
	s_waitcnt lgkmcnt(0)
	v_fma_f32 v22, v22, v94, -v130
	v_fma_f32 v23, v23, v94, -v131
	v_fma_f32 v126, v20, v20, v148
	v_fma_f32 v127, v21, v21, v149
	s_waitcnt vmcnt(2)
	v_lshlrev_b32_e32 v148, 16, v84
	v_and_b32_e32 v149, 0xffff0000, v84
	v_mul_f32_e32 v84, 0xbfb8aa3b, v148
	v_exp_f32_e32 v84, v84
	v_mul_f32_e32 v131, 0xbfb8aa3b, v149
	v_exp_f32_e32 v131, v131
	v_mul_f32_e32 v130, v21, v21
	v_add_f32_e32 v84, 1.0, v84
	v_lshlrev_b32_e32 v150, 16, v85
	v_add_f32 v126, v130, v126
	v_add_f32 v127, v130, v127
	v_rcp_f32_e32 v130, v84
	v_add_f32_e32 v84, 1.0, v131
	v_rcp_f32_e32 v131, v84
	v_and_b32_e32 v151, 0xffff0000, v85
	v_mul_f32_e32 v84, 0xbfb8aa3b, v150
	v_exp_f32_e32 v233, v84
	v_mul_f32_e32 v84, 0xbfb8aa3b, v151
	v_exp_f32_e32 v234, v84
	v_mul_f32 v84, v130, v148
	v_mul_f32 v85, v131, v149
	v_add_f32_e32 v130, 1.0, v233
	v_rcp_f32_e32 v130, v130
	v_add_f32_e32 v131, 1.0, v234
	v_rcp_f32_e32 v131, v131
	v_fma_f32 v26, v26, v94, -v116
	v_fma_f32 v27, v27, v94, -v117
	s_waitcnt vmcnt(1)
	v_lshlrev_b32_e32 v116, 16, v82
	v_fma_f32 v126, v22, v22, v126
	v_fma_f32 v127, v23, v23, v127
	v_mul_f32_e32 v148, v23, v23
	v_and_b32_e32 v117, 0xffff0000, v82
	v_mul_f32_e32 v82, 0xbfb8aa3b, v116
	v_add_f32 v149, v148, v127
	v_add_f32 v148, v148, v126
	v_mul_f32 v126, v130, v150
	v_mul_f32 v127, v131, v151
	v_exp_f32_e32 v82, v82
	v_mul_f32_e32 v130, 0xbfb8aa3b, v117
	v_exp_f32_e32 v130, v130
	v_fma_f32 v24, v24, v94, -v114
	v_fma_f32 v25, v25, v94, -v115
	v_add_f32_e32 v82, 1.0, v82
	v_rcp_f32_e32 v114, v82
	v_add_f32_e32 v82, 1.0, v130
	v_rcp_f32_e32 v115, v82
	v_fma_f32 v130, v24, v24, v148
	v_fma_f32 v131, v25, v25, v149
	v_mul_f32_e32 v82, v25, v25
	v_add_f32 v130, v82, v130
	v_add_f32 v131, v82, v131
	v_lshlrev_b32_e32 v82, 16, v83
	v_mul_f32 v234, v114, v116
	v_mul_f32 v235, v115, v117
	v_mul_f32_e32 v116, 0xbfb8aa3b, v82
	v_exp_f32_e32 v117, v116
	v_fma_f32 v114, v26, v26, v130
	v_fma_f32 v115, v27, v27, v131
	v_mul_f32_e32 v116, v27, v27
	v_fma_f32 v28, v28, v94, -v102
	v_fma_f32 v29, v29, v94, -v103
	v_add_f32 v114, v116, v114
	v_add_f32 v115, v116, v115
	v_fma_f32 v102, v28, v28, v114
	v_fma_f32 v103, v29, v29, v115
	v_mul_f32_e32 v94, v29, v29
	v_add_f32 v102, v94, v102
	v_add_f32 v103, v94, v103
	v_fma_f32 v102, v86, v86, v102
	v_fma_f32 v103, v87, v87, v103
	v_mul_f32_e32 v94, v87, v87
	v_add_f32 v102, v94, v102
	v_add_f32 v103, v94, v103
	v_mov_b32_e32 v94, v102
	s_nop 1
	v_permlane32_swap_b32_e32 v102, v94
	v_add_f32_e32 v94, v102, v94
	v_mov_b32_e32 v102, 0x358637bd
	v_fmamk_f32 v94, v94, 0x3c000000, v102
	s_mov_b32 s2, 0xf800000
	v_mul_f32_e32 v102, 0x4f800000, v94
	v_cmp_gt_f32_e32 vcc, s2, v94
	v_add_f32_e32 v116, 1.0, v117
	v_mul_f32_e32 v70, 0xbfb8aa3b, v68
	v_cndmask_b32_e32 v94, v94, v102, vcc
	v_sqrt_f32_e32 v114, v94
	v_rcp_f32_e32 v102, v116
	v_mul_f32_e32 v71, 0xbfb8aa3b, v69
	v_mul_f32_e32 v58, 0xbfb8aa3b, v56
	v_add_u32_e32 v115, -1, v114
	v_fma_f32 v116, -v115, v114, v94
	v_cmp_ge_f32_e64 s[4:5], 0, v116
	v_add_u32_e32 v116, 1, v114
	v_mul_f32_e32 v59, 0xbfb8aa3b, v57
	v_cndmask_b32_e64 v115, v114, v115, s[4:5]
	v_fma_f32 v114, -v116, v114, v94
	v_mul_f32_e32 v62, 0xbfb8aa3b, v60
	v_mul_f32_e32 v63, 0xbfb8aa3b, v61
	v_cmp_lt_f32_e64 s[4:5], 0, v114
	v_exp_f32_e32 v70, v70
	v_exp_f32_e32 v71, v71
	v_exp_f32_e32 v58, v58
	v_exp_f32_e32 v59, v59
	v_exp_f32_e32 v62, v62
	v_exp_f32_e32 v63, v63
	v_and_b32_e32 v83, 0xffff0000, v83
	v_cndmask_b32_e64 v114, v115, v116, s[4:5]
	v_mul_f32_e32 v117, 0xbfb8aa3b, v83
	v_mul_f32_e32 v115, 0x37800000, v114
	v_exp_f32_e32 v117, v117
	v_cndmask_b32_e32 v114, v114, v115, vcc
	v_cmp_class_f32_e32 vcc, v94, v232
	s_mov_b32 s4, 0x3f4ccccd
	v_add_f32_e32 v48, 1.0, v70
	v_cndmask_b32_e32 v94, v114, v94, vcc
	v_add_f32_e32 v49, 1.0, v71
	v_add_f32_e32 v52, 1.0, v58
	v_add_f32_e32 v53, 1.0, v59
	v_add_f32_e32 v32, 1.0, v62
	v_add_f32_e32 v33, 1.0, v63
	v_div_scale_f32 v130, s[2:3], v94, v94, s4
	v_rcp_f32_e32 v48, v48
	v_rcp_f32_e32 v49, v49
	v_rcp_f32_e32 v52, v52
	v_rcp_f32_e32 v53, v53
	v_rcp_f32_e32 v32, v32
	v_rcp_f32_e32 v33, v33
	v_rcp_f32_e32 v36, v36
	v_rcp_f32_e32 v37, v37
	v_rcp_f32_e32 v42, v42
	v_rcp_f32_e32 v43, v43
	v_rcp_f32_e32 v131, v130
	v_add_f32_e32 v103, 1.0, v117
	v_rcp_f32_e32 v103, v103
	v_add_u32_e32 v0, 0x24800, v0
	ds_read_b128 v[6:9], v0
	ds_read_b128 v[2:5], v0 offset:32
	ds_read_b128 v[64:67], v0 offset:64
	ds_read_b128 v[10:13], v0 offset:96
	v_mul_f32 v186, v48, v68
	v_mul_f32 v187, v49, v69
	ds_read_b128 v[68:71], v0 offset:128
	ds_read_b128 v[48:51], v0 offset:160
	v_mul_f32 v206, v52, v56
	v_mul_f32 v207, v53, v57
	ds_read_b128 v[56:59], v0 offset:192
	ds_read_b128 v[52:55], v0 offset:224
	v_mul_f32 v218, v32, v60
	v_mul_f32 v219, v33, v61
	ds_read_b128 v[60:63], v0 offset:256
	ds_read_b128 v[30:33], v0 offset:288
	v_mul_f32 v222, v36, v40
	v_mul_f32 v223, v37, v41
	ds_read_b128 v[38:41], v0 offset:320
	ds_read_b128 v[34:37], v0 offset:352
	v_mul_f32 v224, v42, v14
	v_mul_f32 v225, v43, v15
	ds_read_b128 v[42:45], v0 offset:384
	ds_read_b128 v[14:17], v0 offset:416
	ds_read_b128 v[114:117], v0 offset:448
	ds_read_b128 v[148:151], v0 offset:480
	v_fma_f32 v0, -v130, v131, 1.0
	v_fmac_f32_e32 v131, v0, v131
	v_div_scale_f32 v0, vcc, s4, v94, s4
	v_mul_f32 v82, v102, v82
	v_mul_f32 v83, v103, v83
	v_mul_f32_e32 v102, v0, v131
	v_fma_f32 v103, -v130, v102, v0
	v_fmac_f32_e32 v102, v103, v131
	v_fma_f32 v0, -v130, v102, v0
	v_div_fmas_f32 v0, v0, v131, v102
	v_div_fixup_f32 v0, v0, v94, s4
	v_mul_f32 v100, v100, v0
	v_mul_f32 v101, v101, v0
	v_mul_f32 v98, v98, v0
	v_mul_f32 v99, v99, v0
	s_waitcnt lgkmcnt(14)
	v_mul_f32 v6, v6, v100
	v_mul_f32 v7, v7, v101
	v_mul_f32 v8, v8, v98
	v_mul_f32 v9, v9, v99
	v_mul_f32 v6, v106, v6
	v_mul_f32 v7, v107, v7
	v_mul_f32 v8, v110, v8
	v_mul_f32 v9, v111, v9
	v_cvt_pk_bf16_f32 v6, v6, v7
	v_cvt_pk_bf16_f32 v7, v8, v9
	global_store_dwordx2 v[88:89], v[6:7], off offset:1024
	v_mul_f32 v6, v112, v0
	v_mul_f32 v7, v113, v0
	s_nop 0
	v_mul_f32 v2, v2, v6
	v_mul_f32 v3, v3, v7
	v_mul_f32 v6, v108, v0
	v_mul_f32 v7, v109, v0
	v_mul_f32 v2, v118, v2
	v_mul_f32 v3, v119, v3
	v_mul_f32 v4, v4, v6
	v_mul_f32 v5, v5, v7
	v_cvt_pk_bf16_f32 v2, v2, v3
	v_mul_f32 v4, v122, v4
	v_mul_f32 v5, v123, v5
	s_waitcnt vmcnt(1)
	v_lshlrev_b32_e32 v6, 16, v80
	v_cvt_pk_bf16_f32 v3, v4, v5
	global_store_dwordx2 v[88:89], v[2:3], off offset:1040
	v_mul_f32 v2, v72, v0
	v_mul_f32 v3, v73, v0
	v_mul_f32 v4, v74, v0
	v_mul_f32 v5, v75, v0
	s_waitcnt lgkmcnt(13)
	v_mul_f32 v2, v64, v2
	v_mul_f32 v3, v65, v3
	v_mul_f32 v4, v66, v4
	v_mul_f32 v5, v67, v5
	v_mul_f32 v2, v124, v2
	v_mul_f32 v3, v125, v3
	v_mul_f32 v4, v128, v4
	v_mul_f32 v5, v129, v5
	v_cvt_pk_bf16_f32 v2, v2, v3
	v_cvt_pk_bf16_f32 v3, v4, v5
	global_store_dwordx2 v[88:89], v[2:3], off offset:1056
	v_mul_f32 v2, v76, v0
	v_mul_f32 v3, v77, v0
	v_mul_f32 v4, v78, v0
	v_mul_f32 v5, v79, v0
	s_waitcnt lgkmcnt(12)
	v_mul_f32 v2, v2, v10
	v_mul_f32 v3, v3, v11
	v_mul_f32 v4, v4, v12
	v_mul_f32 v5, v5, v13
	v_mul_f32 v2, v134, v2
	v_mul_f32 v3, v135, v3
	v_mul_f32 v4, v138, v4
	v_mul_f32 v5, v139, v5
	v_cvt_pk_bf16_f32 v2, v2, v3
	v_cvt_pk_bf16_f32 v3, v4, v5
	global_store_dwordx2 v[88:89], v[2:3], off offset:1072
	v_mul_f32 v2, v140, v0
	v_mul_f32 v3, v141, v0
	v_mul_f32 v4, v136, v0
	v_mul_f32 v5, v137, v0
	s_waitcnt lgkmcnt(11)
	v_mul_f32 v2, v2, v68
	v_mul_f32 v3, v3, v69
	v_mul_f32 v4, v4, v70
	v_mul_f32 v5, v5, v71
	v_mul_f32 v2, v178, v2
	v_mul_f32 v3, v179, v3
	v_mul_f32 v4, v186, v4
	v_mul_f32 v5, v187, v5
	v_cvt_pk_bf16_f32 v2, v2, v3
	v_cvt_pk_bf16_f32 v3, v4, v5
	global_store_dwordx2 v[88:89], v[2:3], off offset:1088
	v_mul_f32 v2, v188, v0
	v_mul_f32 v3, v189, v0
	v_mul_f32 v4, v184, v0
	v_mul_f32 v5, v185, v0
	s_waitcnt lgkmcnt(10)
	v_mul_f32 v2, v2, v48
	v_mul_f32 v3, v3, v49
	v_mul_f32 v4, v4, v50
	v_mul_f32 v5, v5, v51
	v_mul_f32 v2, v146, v2
	v_mul_f32 v3, v147, v3
	v_mul_f32 v4, v194, v4
	v_mul_f32 v5, v195, v5
	v_cvt_pk_bf16_f32 v2, v2, v3
	v_cvt_pk_bf16_f32 v3, v4, v5
	global_store_dwordx2 v[88:89], v[2:3], off offset:1104
	v_mul_f32 v2, v200, v0
	v_mul_f32 v3, v201, v0
	v_mul_f32 v4, v192, v0
	v_mul_f32 v5, v193, v0
	s_waitcnt lgkmcnt(9)
	v_mul_f32 v2, v2, v56
	v_mul_f32 v3, v3, v57
	v_mul_f32 v4, v4, v58
	v_mul_f32 v5, v5, v59
	v_mul_f32 v2, v132, v2
	v_mul_f32 v3, v133, v3
	v_mul_f32 v4, v206, v4
	v_mul_f32 v5, v207, v5
	v_cvt_pk_bf16_f32 v2, v2, v3
	v_cvt_pk_bf16_f32 v3, v4, v5
	global_store_dwordx2 v[88:89], v[2:3], off offset:1120
	v_mul_f32 v2, v210, v0
	v_mul_f32 v3, v211, v0
	v_mul_f32 v4, v202, v0
	v_mul_f32 v5, v203, v0
	s_waitcnt lgkmcnt(8)
	v_mul_f32 v2, v2, v52
	v_mul_f32 v3, v3, v53
	v_mul_f32 v4, v4, v54
	v_mul_f32 v5, v5, v55
	v_mul_f32 v2, v120, v2
	v_mul_f32 v3, v121, v3
	v_mul_f32 v4, v214, v4
	v_mul_f32 v5, v215, v5
	v_cvt_pk_bf16_f32 v2, v2, v3
	v_cvt_pk_bf16_f32 v3, v4, v5
	global_store_dwordx2 v[88:89], v[2:3], off offset:1136
	v_mul_f32 v2, v216, v0
	v_mul_f32 v3, v217, v0
	v_mul_f32 v4, v212, v0
	v_mul_f32 v5, v213, v0
	s_waitcnt lgkmcnt(7)
	v_mul_f32 v2, v2, v60
	v_mul_f32 v3, v3, v61
	v_mul_f32 v4, v4, v62
	v_mul_f32 v5, v5, v63
	v_mul_f32 v2, v104, v2
	v_mul_f32 v3, v105, v3
	v_mul_f32 v4, v218, v4
	v_mul_f32 v5, v219, v5
	v_cvt_pk_bf16_f32 v2, v2, v3
	v_cvt_pk_bf16_f32 v3, v4, v5
	global_store_dwordx2 v[88:89], v[2:3], off offset:1152
	v_mul_f32 v2, v204, v0
	v_mul_f32 v3, v205, v0
	v_mul_f32 v4, v208, v0
	v_mul_f32 v5, v209, v0
	s_waitcnt lgkmcnt(6)
	v_mul_f32 v2, v2, v30
	v_mul_f32 v3, v3, v31
	v_mul_f32 v4, v4, v32
	v_mul_f32 v5, v5, v33
	v_mul_f32 v2, v96, v2
	v_mul_f32 v3, v97, v3
	v_mul_f32 v4, v220, v4
	v_mul_f32 v5, v221, v5
	v_cvt_pk_bf16_f32 v2, v2, v3
	v_cvt_pk_bf16_f32 v3, v4, v5
	global_store_dwordx2 v[88:89], v[2:3], off offset:1168
	v_mul_f32 v2, v190, v0
	v_mul_f32 v3, v191, v0
	v_mul_f32 v4, v198, v0
	v_mul_f32 v5, v199, v0
	s_waitcnt lgkmcnt(5)
	v_mul_f32 v2, v2, v38
	v_mul_f32 v3, v3, v39
	v_mul_f32 v4, v4, v40
	v_mul_f32 v5, v5, v41
	v_mul_f32 v2, v92, v2
	v_mul_f32 v3, v93, v3
	v_mul_f32 v4, v222, v4
	v_mul_f32 v5, v223, v5
	v_cvt_pk_bf16_f32 v2, v2, v3
	v_cvt_pk_bf16_f32 v3, v4, v5
	global_store_dwordx2 v[88:89], v[2:3], off offset:1184
	v_mul_f32 v2, v180, v0
	v_mul_f32 v3, v181, v0
	v_mul_f32 v4, v46, v0
	v_mul_f32 v5, v47, v0
	s_waitcnt lgkmcnt(4)
	v_mul_f32 v2, v2, v34
	v_mul_f32 v3, v3, v35
	v_mul_f32 v4, v4, v36
	v_mul_f32 v5, v5, v37
	v_mul_f32 v2, v90, v2
	v_mul_f32 v3, v91, v3
	v_mul_f32 v4, v182, v4
	v_mul_f32 v5, v183, v5
	v_cvt_pk_bf16_f32 v2, v2, v3
	v_cvt_pk_bf16_f32 v3, v4, v5
	global_store_dwordx2 v[88:89], v[2:3], off offset:1200
	v_mul_f32 v2, v142, v0
	v_mul_f32 v3, v143, v0
	v_mul_f32 v4, v18, v0
	v_mul_f32 v5, v19, v0
	s_waitcnt lgkmcnt(3)
	v_mul_f32 v2, v2, v42
	v_mul_f32 v3, v3, v43
	v_mul_f32 v4, v4, v44
	v_mul_f32 v5, v5, v45
	v_mul_f32 v2, v144, v2
	v_mul_f32 v3, v145, v3
	v_mul_f32 v4, v224, v4
	v_mul_f32 v5, v225, v5
	v_cvt_pk_bf16_f32 v2, v2, v3
	v_cvt_pk_bf16_f32 v3, v4, v5
	global_store_dwordx2 v[88:89], v[2:3], off offset:1216
	v_mul_f32 v2, v20, v0
	v_mul_f32 v3, v21, v0
	v_mul_f32 v4, v22, v0
	v_mul_f32 v5, v23, v0
	s_waitcnt lgkmcnt(2)
	v_mul_f32 v2, v2, v14
	v_mul_f32 v3, v3, v15
	v_mul_f32 v4, v4, v16
	v_mul_f32 v5, v5, v17
	v_mul_f32 v2, v84, v2
	v_mul_f32 v3, v85, v3
	v_mul_f32 v4, v126, v4
	v_mul_f32 v5, v127, v5
	v_cvt_pk_bf16_f32 v2, v2, v3
	v_cvt_pk_bf16_f32 v3, v4, v5
	global_store_dwordx2 v[88:89], v[2:3], off offset:1232
	v_mul_f32 v2, v24, v0
	v_mul_f32 v3, v25, v0
	v_and_b32_e32 v7, 0xffff0000, v80
	s_waitcnt lgkmcnt(1)
	v_mul_f32 v2, v2, v114
	v_mul_f32 v3, v3, v115
	v_mul_f32 v4, v26, v0
	v_mul_f32 v5, v27, v0
	v_mul_f32 v2, v234, v2
	v_mul_f32 v3, v235, v3
	v_mul_f32 v4, v4, v116
	v_mul_f32 v5, v5, v117
	v_cvt_pk_bf16_f32 v2, v2, v3
	v_mul_f32_e32 v3, 0xbfb8aa3b, v6
	v_exp_f32_e32 v8, v3
	v_mul_f32_e32 v3, 0xbfb8aa3b, v7
	v_exp_f32_e32 v9, v3
	v_mul_f32 v4, v82, v4
	v_mul_f32 v5, v83, v5
	s_nop 0
	v_cvt_pk_bf16_f32 v3, v4, v5
	v_add_f32_e32 v4, 1.0, v8
	v_add_f32_e32 v5, 1.0, v9
	v_rcp_f32_e32 v4, v4
	v_rcp_f32_e32 v5, v5
	global_store_dwordx2 v[88:89], v[2:3], off offset:1248
	v_mul_f32 v2, v28, v0
	v_mul_f32 v3, v29, v0
	v_mul_f32 v4, v4, v6
	v_mul_f32 v5, v5, v7
	v_lshlrev_b32_e32 v6, 16, v81
	v_and_b32_e32 v7, 0xffff0000, v81
	v_mul_f32_e32 v8, 0xbfb8aa3b, v6
	v_mul_f32_e32 v9, 0xbfb8aa3b, v7
	v_exp_f32_e32 v8, v8
	v_exp_f32_e32 v9, v9
	s_waitcnt lgkmcnt(0)
	v_mul_f32 v2, v2, v148
	v_mul_f32 v3, v3, v149
	s_nop 0
	v_mul_f32 v2, v4, v2
	v_mul_f32 v3, v5, v3
	v_add_f32_e32 v4, 1.0, v8
	v_add_f32_e32 v5, 1.0, v9
	v_rcp_f32_e32 v4, v4
	v_rcp_f32_e32 v5, v5
	v_mul_f32 v8, v86, v0
	v_mul_f32 v9, v87, v0
	v_cvt_pk_bf16_f32 v2, v2, v3
	v_mul_f32 v8, v8, v150
	v_mul_f32 v9, v9, v151
	v_mul_f32 v4, v4, v6
	v_mul_f32 v5, v5, v7
	s_nop 0
	v_mul_f32 v4, v4, v8
	v_mul_f32 v5, v5, v9
	s_nop 0
	v_cvt_pk_bf16_f32 v3, v4, v5
	global_store_dwordx2 v[88:89], v[2:3], off offset:1264
	s_branch .LBB0_299
